# v46 + loop-edge trimming: two dead scalar ops removed, loop compare hoisted into slot-15 QK shadow so only the branch sits between last filler and next QK MFMA
# speedup vs baseline: 1.0015x; 1.0015x over previous
.Latt_loop:
	s_waitcnt lgkmcnt(5)
	v_mfma_f32_32x32x16_bf16 v[98:113], v[238:241], v[134:137], 0
	v_exp_f32_e32 v66, v66
	v_exp_f32_e32 v67, v67
	v_exp_f32_e32 v68, v68
	s_add_i32 s13, s12, 1
	s_cmp_eq_u32 s12, 2
	s_cselect_b32 s12, 0, s13
	s_mul_i32 s15, s12, 0x4800
	s_mul_i32 s16, s12, 0x6000
	s_add_i32 s16, s16, 0xd800
	s_add_i32 s17, s14, 2
	s_min_u32 s17, s17, s11
	s_lshl_b32 s64, s17, 17
	s_add_i32 s14, s14, 1
	v_mfma_f32_32x32x16_bf16 v[34:49], v[182:185], v[118:121], v[34:49]
	v_exp_f32_e32 v69, v69
	v_exp_f32_e32 v70, v70
	v_exp_f32_e32 v71, v71
	v_mov_b32_e32 v250, v251
	v_add3_u32 v251, s15, v236, v210
	v_mov_b32_e32 v252, v215
	v_add_u32_e32 v215, s16, v232
	ds_read_b128 v[238:241], v250 offset:4672
	ds_read_b64_tr_b16 v[182:183], v252 offset:3072
	ds_read_b64_tr_b16 v[184:185], v252 offset:4608
	v_mfma_f32_32x32x16_bf16 v[50:65], v[186:189], v[118:121], v[50:65]
	v_exp_f32_e32 v72, v72
	v_exp_f32_e32 v73, v73
	v_cvt_pk_bf16_f32 v66, v66, v67
	v_cvt_pk_bf16_f32 v67, v68, v69
	ds_read_b64_tr_b16 v[186:187], v252 offset:3136
	ds_read_b64_tr_b16 v[188:189], v252 offset:4672
	v_mfma_f32_16x16x32_bf16 v[170:173], v[130:133], v[118:121], v[170:173]
	v_cvt_pk_bf16_f32 v68, v70, v71
	v_cvt_pk_bf16_f32 v69, v72, v73
	s_waitcnt lgkmcnt(5)
	v_mfma_f32_32x32x16_bf16 v[98:113], v[242:245], v[138:141], v[98:113]
	v_exp_f32_e32 v82, v82
	v_exp_f32_e32 v83, v83
	v_exp_f32_e32 v84, v84
	ds_read_b128 v[242:245], v250 offset:4704
	s_waitcnt vmcnt(0)
	v_add_u32_e32 v246, s15, v204
	v_add_u32_e32 v247, s16, v231
	ds_write_b128 v246, v[158:161]
	ds_write_b128 v246, v[162:165] offset:9216
	v_mfma_f32_32x32x16_bf16 v[2:17], v[174:177], v[66:69], v[2:17]
	v_exp_f32_e32 v85, v85
	v_exp_f32_e32 v86, v86
	v_exp_f32_e32 v87, v87
	ds_write_b128 v247, v[150:153]
	ds_write_b128 v247, v[154:157] offset:12288
	v_mfma_f32_32x32x16_bf16 v[18:33], v[178:181], v[66:69], v[18:33]
	v_exp_f32_e32 v88, v88
	v_exp_f32_e32 v89, v89
	v_cvt_pk_bf16_f32 v82, v82, v83
	v_cvt_pk_bf16_f32 v83, v84, v85
	s_add_u32 s18, s100, s64
	s_addc_u32 s19, s101, 0
	global_load_dwordx4 v[158:161], v248, s[18:19]
	global_load_dwordx4 v[162:165], v249, s[18:19]
	v_mfma_f32_16x16x32_bf16 v[166:169], v[130:133], v[66:69], v[166:169]
	v_cvt_pk_bf16_f32 v84, v86, v87
	v_cvt_pk_bf16_f32 v85, v88, v89
	s_waitcnt lgkmcnt(9)
	v_mfma_f32_32x32x16_bf16 v[114:129], v[238:241], v[142:145], 0
	v_exp_f32_e32 v74, v74
	v_exp_f32_e32 v75, v75
	v_exp_f32_e32 v76, v76
	ds_read_b128 v[238:241], v250 offset:9216
	v_mfma_f32_32x32x16_bf16 v[34:49], v[174:177], v[82:85], v[34:49]
	v_exp_f32_e32 v77, v77
	v_exp_f32_e32 v78, v78
	v_exp_f32_e32 v79, v79
	ds_read_b64_tr_b16 v[174:175], v252 offset:6144
	ds_read_b64_tr_b16 v[176:177], v252 offset:7680
	v_mfma_f32_32x32x16_bf16 v[50:65], v[178:181], v[82:85], v[50:65]
	v_exp_f32_e32 v80, v80
	v_exp_f32_e32 v81, v81
	v_cvt_pk_bf16_f32 v70, v74, v75
	v_cvt_pk_bf16_f32 v71, v76, v77
	ds_read_b64_tr_b16 v[178:179], v252 offset:6208
	ds_read_b64_tr_b16 v[180:181], v252 offset:7744
	v_mfma_f32_16x16x32_bf16 v[170:173], v[130:133], v[82:85], v[170:173]
	v_cvt_pk_bf16_f32 v72, v78, v79
	v_cvt_pk_bf16_f32 v73, v80, v81
	s_waitcnt lgkmcnt(9)
	v_mfma_f32_32x32x16_bf16 v[114:129], v[242:245], v[146:149], v[114:129]
	v_exp_f32_e32 v90, v90
	v_exp_f32_e32 v91, v91
	v_exp_f32_e32 v92, v92
	ds_read_b128 v[242:245], v250 offset:9248
	v_mfma_f32_32x32x16_bf16 v[2:17], v[182:185], v[70:73], v[2:17]
	v_exp_f32_e32 v93, v93
	v_exp_f32_e32 v94, v94
	v_exp_f32_e32 v95, v95
	s_add_u32 s18, s18, 0x1040000
	s_addc_u32 s19, s19, 0
	global_load_dwordx4 v[150:153], v248, s[18:19]
	global_load_dwordx4 v[154:157], v249, s[18:19]
	v_mfma_f32_32x32x16_bf16 v[18:33], v[186:189], v[70:73], v[18:33]
	v_exp_f32_e32 v96, v96
	v_exp_f32_e32 v97, v97
	v_cvt_pk_bf16_f32 v86, v90, v91
	v_cvt_pk_bf16_f32 v87, v92, v93
	v_mfma_f32_16x16x32_bf16 v[166:169], v[130:133], v[70:73], v[166:169]
	v_cvt_pk_bf16_f32 v88, v94, v95
	v_cvt_pk_bf16_f32 v89, v96, v97
	s_waitcnt lgkmcnt(5)
	v_mfma_f32_32x32x16_bf16 v[66:81], v[238:241], v[134:137], 0
	v_exp_f32_e32 v98, v98
	v_exp_f32_e32 v99, v99
	v_exp_f32_e32 v100, v100
	ds_read_b128 v[238:241], v250 offset:9280
	v_mfma_f32_32x32x16_bf16 v[34:49], v[182:185], v[86:89], v[34:49]
	v_exp_f32_e32 v101, v101
	v_exp_f32_e32 v102, v102
	v_exp_f32_e32 v103, v103
	ds_read_b64_tr_b16 v[182:183], v252 offset:9216
	ds_read_b64_tr_b16 v[184:185], v252 offset:10752
	v_mfma_f32_32x32x16_bf16 v[50:65], v[186:189], v[86:89], v[50:65]
	v_exp_f32_e32 v104, v104
	v_exp_f32_e32 v105, v105
	v_cvt_pk_bf16_f32 v98, v98, v99
	v_cvt_pk_bf16_f32 v99, v100, v101
	ds_read_b64_tr_b16 v[186:187], v252 offset:9280
	ds_read_b64_tr_b16 v[188:189], v252 offset:10816
	v_mfma_f32_16x16x32_bf16 v[170:173], v[130:133], v[86:89], v[170:173]
	v_cvt_pk_bf16_f32 v100, v102, v103
	v_cvt_pk_bf16_f32 v101, v104, v105
	s_waitcnt lgkmcnt(5)
	v_mfma_f32_32x32x16_bf16 v[66:81], v[242:245], v[138:141], v[66:81]
	v_exp_f32_e32 v114, v114
	v_exp_f32_e32 v115, v115
	v_exp_f32_e32 v116, v116
	ds_read_b128 v[242:245], v250 offset:9312
	v_mfma_f32_32x32x16_bf16 v[2:17], v[174:177], v[98:101], v[2:17]
	v_exp_f32_e32 v117, v117
	v_exp_f32_e32 v118, v118
	v_exp_f32_e32 v119, v119
	v_mfma_f32_32x32x16_bf16 v[18:33], v[178:181], v[98:101], v[18:33]
	v_exp_f32_e32 v120, v120
	v_exp_f32_e32 v121, v121
	v_cvt_pk_bf16_f32 v114, v114, v115
	v_cvt_pk_bf16_f32 v115, v116, v117
	v_mfma_f32_16x16x32_bf16 v[166:169], v[130:133], v[98:101], v[166:169]
	v_cvt_pk_bf16_f32 v116, v118, v119
	v_cvt_pk_bf16_f32 v117, v120, v121
	s_waitcnt lgkmcnt(5)
	v_mfma_f32_32x32x16_bf16 v[82:97], v[238:241], v[142:145], 0
	v_exp_f32_e32 v106, v106
	v_exp_f32_e32 v107, v107
	v_exp_f32_e32 v108, v108
	ds_read_b128 v[238:241], v250 offset:13824
	v_mfma_f32_32x32x16_bf16 v[34:49], v[174:177], v[114:117], v[34:49]
	v_exp_f32_e32 v109, v109
	v_exp_f32_e32 v110, v110
	v_exp_f32_e32 v111, v111
	ds_read_b64_tr_b16 v[174:175], v252 offset:12288
	ds_read_b64_tr_b16 v[176:177], v252 offset:13824
	v_mfma_f32_32x32x16_bf16 v[50:65], v[178:181], v[114:117], v[50:65]
	v_exp_f32_e32 v112, v112
	v_exp_f32_e32 v113, v113
	v_cvt_pk_bf16_f32 v102, v106, v107
	v_cvt_pk_bf16_f32 v103, v108, v109
	ds_read_b64_tr_b16 v[178:179], v252 offset:12352
	ds_read_b64_tr_b16 v[180:181], v252 offset:13888
	v_mfma_f32_16x16x32_bf16 v[170:173], v[130:133], v[114:117], v[170:173]
	v_cvt_pk_bf16_f32 v104, v110, v111
	v_cvt_pk_bf16_f32 v105, v112, v113
	s_waitcnt lgkmcnt(5)
	v_mfma_f32_32x32x16_bf16 v[82:97], v[242:245], v[146:149], v[82:97]
	v_exp_f32_e32 v122, v122
	v_exp_f32_e32 v123, v123
	v_exp_f32_e32 v124, v124
	ds_read_b128 v[242:245], v250 offset:13856
	v_mfma_f32_32x32x16_bf16 v[2:17], v[182:185], v[102:105], v[2:17]
	v_exp_f32_e32 v125, v125
	v_exp_f32_e32 v126, v126
	v_exp_f32_e32 v127, v127
	v_mfma_f32_32x32x16_bf16 v[18:33], v[186:189], v[102:105], v[18:33]
	v_exp_f32_e32 v128, v128
	v_exp_f32_e32 v129, v129
	v_cvt_pk_bf16_f32 v118, v122, v123
	v_cvt_pk_bf16_f32 v119, v124, v125
	v_mfma_f32_16x16x32_bf16 v[166:169], v[130:133], v[102:105], v[166:169]
	v_cvt_pk_bf16_f32 v120, v126, v127
	v_cvt_pk_bf16_f32 v121, v128, v129
	s_waitcnt lgkmcnt(5)
	v_mfma_f32_32x32x16_bf16 v[98:113], v[238:241], v[134:137], 0
	v_exp_f32_e32 v66, v66
	v_exp_f32_e32 v67, v67
	v_exp_f32_e32 v68, v68
	ds_read_b128 v[238:241], v250 offset:13888
	v_mfma_f32_32x32x16_bf16 v[34:49], v[182:185], v[118:121], v[34:49]
	v_exp_f32_e32 v69, v69
	v_exp_f32_e32 v70, v70
	v_exp_f32_e32 v71, v71
	ds_read_b64_tr_b16 v[182:183], v252 offset:15360
	ds_read_b64_tr_b16 v[184:185], v252 offset:16896
	v_mfma_f32_32x32x16_bf16 v[50:65], v[186:189], v[118:121], v[50:65]
	v_exp_f32_e32 v72, v72
	v_exp_f32_e32 v73, v73
	v_cvt_pk_bf16_f32 v66, v66, v67
	v_cvt_pk_bf16_f32 v67, v68, v69
	ds_read_b64_tr_b16 v[186:187], v252 offset:15424
	ds_read_b64_tr_b16 v[188:189], v252 offset:16960
	v_mfma_f32_16x16x32_bf16 v[170:173], v[130:133], v[118:121], v[170:173]
	v_cvt_pk_bf16_f32 v68, v70, v71
	v_cvt_pk_bf16_f32 v69, v72, v73
	s_waitcnt lgkmcnt(5)
	v_mfma_f32_32x32x16_bf16 v[98:113], v[242:245], v[138:141], v[98:113]
	v_exp_f32_e32 v82, v82
	v_exp_f32_e32 v83, v83
	v_exp_f32_e32 v84, v84
	ds_read_b128 v[242:245], v250 offset:13920
	v_mfma_f32_32x32x16_bf16 v[2:17], v[174:177], v[66:69], v[2:17]
	v_exp_f32_e32 v85, v85
	v_exp_f32_e32 v86, v86
	v_exp_f32_e32 v87, v87
	v_mfma_f32_32x32x16_bf16 v[18:33], v[178:181], v[66:69], v[18:33]
	v_exp_f32_e32 v88, v88
	v_exp_f32_e32 v89, v89
	v_cvt_pk_bf16_f32 v82, v82, v83
	v_cvt_pk_bf16_f32 v83, v84, v85
	v_mfma_f32_16x16x32_bf16 v[166:169], v[130:133], v[66:69], v[166:169]
	v_cvt_pk_bf16_f32 v84, v86, v87
	v_cvt_pk_bf16_f32 v85, v88, v89
	s_barrier
	s_waitcnt lgkmcnt(5)
	v_mfma_f32_32x32x16_bf16 v[114:129], v[238:241], v[142:145], 0
	v_exp_f32_e32 v74, v74
	v_exp_f32_e32 v75, v75
	v_exp_f32_e32 v76, v76
	ds_read_b128 v[238:241], v251
	v_mfma_f32_32x32x16_bf16 v[34:49], v[174:177], v[82:85], v[34:49]
	v_exp_f32_e32 v77, v77
	v_exp_f32_e32 v78, v78
	v_exp_f32_e32 v79, v79
	ds_read_b64_tr_b16 v[174:175], v252 offset:18432
	ds_read_b64_tr_b16 v[176:177], v252 offset:19968
	v_mfma_f32_32x32x16_bf16 v[50:65], v[178:181], v[82:85], v[50:65]
	v_exp_f32_e32 v80, v80
	v_exp_f32_e32 v81, v81
	v_cvt_pk_bf16_f32 v70, v74, v75
	v_cvt_pk_bf16_f32 v71, v76, v77
	ds_read_b64_tr_b16 v[178:179], v252 offset:18496
	ds_read_b64_tr_b16 v[180:181], v252 offset:20032
	v_mfma_f32_16x16x32_bf16 v[170:173], v[130:133], v[82:85], v[170:173]
	v_cvt_pk_bf16_f32 v72, v78, v79
	v_cvt_pk_bf16_f32 v73, v80, v81
	s_waitcnt lgkmcnt(5)
	v_mfma_f32_32x32x16_bf16 v[114:129], v[242:245], v[146:149], v[114:129]
	v_exp_f32_e32 v90, v90
	v_exp_f32_e32 v91, v91
	v_exp_f32_e32 v92, v92
	ds_read_b128 v[242:245], v251 offset:32
	v_mfma_f32_32x32x16_bf16 v[2:17], v[182:185], v[70:73], v[2:17]
	v_exp_f32_e32 v93, v93
	v_exp_f32_e32 v94, v94
	v_exp_f32_e32 v95, v95
	v_mfma_f32_32x32x16_bf16 v[18:33], v[186:189], v[70:73], v[18:33]
	v_exp_f32_e32 v96, v96
	v_exp_f32_e32 v97, v97
	v_cvt_pk_bf16_f32 v86, v90, v91
	v_cvt_pk_bf16_f32 v87, v92, v93
	v_mfma_f32_16x16x32_bf16 v[166:169], v[130:133], v[70:73], v[166:169]
	v_cvt_pk_bf16_f32 v88, v94, v95
	v_cvt_pk_bf16_f32 v89, v96, v97
	s_waitcnt lgkmcnt(5)
	v_mfma_f32_32x32x16_bf16 v[66:81], v[238:241], v[134:137], 0
	v_exp_f32_e32 v98, v98
	v_exp_f32_e32 v99, v99
	v_exp_f32_e32 v100, v100
	ds_read_b128 v[238:241], v251 offset:64
	v_mfma_f32_32x32x16_bf16 v[34:49], v[182:185], v[86:89], v[34:49]
	v_exp_f32_e32 v101, v101
	v_exp_f32_e32 v102, v102
	v_exp_f32_e32 v103, v103
	ds_read_b64_tr_b16 v[182:183], v252 offset:21504
	ds_read_b64_tr_b16 v[184:185], v252 offset:23040
	v_mfma_f32_32x32x16_bf16 v[50:65], v[186:189], v[86:89], v[50:65]
	v_exp_f32_e32 v104, v104
	v_exp_f32_e32 v105, v105
	v_cvt_pk_bf16_f32 v98, v98, v99
	v_cvt_pk_bf16_f32 v99, v100, v101
	ds_read_b64_tr_b16 v[186:187], v252 offset:21568
	ds_read_b64_tr_b16 v[188:189], v252 offset:23104
	v_mfma_f32_16x16x32_bf16 v[170:173], v[130:133], v[86:89], v[170:173]
	v_cvt_pk_bf16_f32 v100, v102, v103
	v_cvt_pk_bf16_f32 v101, v104, v105
	s_waitcnt lgkmcnt(5)
	v_mfma_f32_32x32x16_bf16 v[66:81], v[242:245], v[138:141], v[66:81]
	v_exp_f32_e32 v114, v114
	v_exp_f32_e32 v115, v115
	v_exp_f32_e32 v116, v116
	ds_read_b128 v[242:245], v251 offset:96
	v_mfma_f32_32x32x16_bf16 v[2:17], v[174:177], v[98:101], v[2:17]
	v_exp_f32_e32 v117, v117
	v_exp_f32_e32 v118, v118
	v_exp_f32_e32 v119, v119
	v_mfma_f32_32x32x16_bf16 v[18:33], v[178:181], v[98:101], v[18:33]
	v_exp_f32_e32 v120, v120
	v_exp_f32_e32 v121, v121
	v_cvt_pk_bf16_f32 v114, v114, v115
	v_cvt_pk_bf16_f32 v115, v116, v117
	v_mfma_f32_16x16x32_bf16 v[166:169], v[130:133], v[98:101], v[166:169]
	v_cvt_pk_bf16_f32 v116, v118, v119
	v_cvt_pk_bf16_f32 v117, v120, v121
	s_waitcnt lgkmcnt(5)
	v_mfma_f32_32x32x16_bf16 v[82:97], v[238:241], v[142:145], 0
	v_exp_f32_e32 v106, v106
	v_exp_f32_e32 v107, v107
	v_exp_f32_e32 v108, v108
	ds_read_b128 v[238:241], v251 offset:4608
	v_mfma_f32_32x32x16_bf16 v[34:49], v[174:177], v[114:117], v[34:49]
	v_exp_f32_e32 v109, v109
	v_exp_f32_e32 v110, v110
	v_exp_f32_e32 v111, v111
	ds_read_b64_tr_b16 v[174:175], v215
	ds_read_b64_tr_b16 v[176:177], v215 offset:1536
	v_mfma_f32_32x32x16_bf16 v[50:65], v[178:181], v[114:117], v[50:65]
	v_exp_f32_e32 v112, v112
	v_exp_f32_e32 v113, v113
	v_cvt_pk_bf16_f32 v102, v106, v107
	v_cvt_pk_bf16_f32 v103, v108, v109
	ds_read_b64_tr_b16 v[178:179], v215 offset:64
	ds_read_b64_tr_b16 v[180:181], v215 offset:1600
	v_mfma_f32_16x16x32_bf16 v[170:173], v[130:133], v[114:117], v[170:173]
	v_cvt_pk_bf16_f32 v104, v110, v111
	v_cvt_pk_bf16_f32 v105, v112, v113
	s_waitcnt lgkmcnt(5)
	v_mfma_f32_32x32x16_bf16 v[82:97], v[242:245], v[146:149], v[82:97]
	v_exp_f32_e32 v122, v122
	v_exp_f32_e32 v123, v123
	v_exp_f32_e32 v124, v124
	ds_read_b128 v[242:245], v251 offset:4640
	s_cmp_lg_u32 s14, s10
	v_mfma_f32_32x32x16_bf16 v[2:17], v[182:185], v[102:105], v[2:17]
	v_exp_f32_e32 v125, v125
	v_exp_f32_e32 v126, v126
	v_exp_f32_e32 v127, v127
	v_mfma_f32_32x32x16_bf16 v[18:33], v[186:189], v[102:105], v[18:33]
	v_exp_f32_e32 v128, v128
	v_exp_f32_e32 v129, v129
	v_cvt_pk_bf16_f32 v118, v122, v123
	v_cvt_pk_bf16_f32 v119, v124, v125
	v_mfma_f32_16x16x32_bf16 v[166:169], v[130:133], v[102:105], v[166:169]
	v_cvt_pk_bf16_f32 v120, v126, v127
	v_cvt_pk_bf16_f32 v121, v128, v129
	s_cbranch_scc1 .Latt_loop
	s_waitcnt lgkmcnt(0)
	s_nop 1
	v_mfma_f32_16x16x32_bf16 v[170:173], v[130:133], v[118:121], v[170:173]
	v_mfma_f32_32x32x16_bf16 v[34:49], v[182:185], v[118:121], v[34:49]
	v_mfma_f32_32x32x16_bf16 v[50:65], v[186:189], v[118:121], v[50:65]
	s_nop 11
	global_load_dwordx4 v[98:101], v[212:213], off offset:32
	global_load_dwordx4 v[102:105], v[212:213], off offset:64
	global_load_dwordx4 v[106:109], v[212:213], off offset:96
	global_load_dwordx4 v[110:113], v[212:213], off offset:128
	global_load_dwordx4 v[114:117], v[212:213], off offset:160
	global_load_dwordx4 v[122:125], v[212:213], off offset:192
	global_load_dwordx4 v[126:129], v[212:213], off offset:224
	ds_bpermute_b32 v66, v237, v166
	s_nop 3
	ds_bpermute_b32 v67, v237, v170
	s_lshl_b32 s64, s9, 1
	v_mov_b32_e32 v215, v191
	s_mov_b32 s2, 0xf226000
	s_waitcnt lgkmcnt(1)
	v_div_scale_f32 v68, s[10:11], v66, v66, 1.0
	v_rcp_f32_e32 v69, v68
	s_add_i32 s8, s8, 1
	s_cmp_eq_u32 s8, s7
	v_fma_f32 v70, -v68, v69, 1.0
	v_fmac_f32_e32 v69, v70, v69
	v_div_scale_f32 v70, vcc, 1.0, v66, 1.0
	v_mul_f32_e32 v71, v70, v69
	v_fma_f32 v72, -v68, v71, v70
	v_fmac_f32_e32 v71, v72, v69
	v_fma_f32 v68, -v68, v71, v70
	v_div_fmas_f32 v68, v68, v69, v71
	v_div_fixup_f32 v66, v68, v66, 1.0
	s_waitcnt lgkmcnt(0)
	v_div_scale_f32 v68, s[10:11], v67, v67, v230
	v_rcp_f32_e32 v69, v68
	s_mov_b64 s[10:11], 0xf226400
	v_fma_f32 v70, -v68, v69, 1.0
	v_fmac_f32_e32 v69, v70, v69
	v_div_scale_f32 v70, vcc, v230, v67, v230
	v_mul_f32_e32 v71, v70, v69
	v_fma_f32 v72, -v68, v71, v70
	v_fmac_f32_e32 v71, v72, v69
	v_fma_f32 v68, -v68, v71, v70
	v_div_fmas_f32 v68, v68, v69, v71
	v_div_fixup_f32 v68, v68, v67, v230
	v_pk_mul_f32 v[62:63], v[62:63], v[68:69] op_sel_hi:[1,0]
	v_pk_mul_f32 v[34:35], v[34:35], v[68:69] op_sel_hi:[1,0]
	v_pk_fma_f32 v[30:31], v[30:31], v[66:67], v[62:63] op_sel_hi:[1,0,1] neg_lo:[0,0,1] neg_hi:[0,0,1]
	v_pk_mul_f32 v[62:63], v[64:65], v[68:69] op_sel_hi:[1,0]
	v_pk_mul_f32 v[36:37], v[36:37], v[68:69] op_sel_hi:[1,0]
	v_pk_fma_f32 v[32:33], v[32:33], v[66:67], v[62:63] op_sel_hi:[1,0,1] neg_lo:[0,0,1] neg_hi:[0,0,1]
	v_lshlrev_b64 v[62:63], 11, v[216:217]
	v_lshl_add_u64 v[62:63], s[54:55], 0, v[62:63]
	v_lshl_add_u64 v[74:75], v[62:63], 0, s[64:65]
	global_load_dwordx4 v[62:65], v[212:213], off
	v_pk_fma_f32 v[34:35], v[2:3], v[66:67], v[34:35] op_sel_hi:[1,0,1] neg_lo:[0,0,1] neg_hi:[0,0,1]
	v_pk_fma_f32 v[4:5], v[4:5], v[66:67], v[36:37] op_sel_hi:[1,0,1] neg_lo:[0,0,1] neg_hi:[0,0,1]
	v_pk_mul_f32 v[76:77], v[34:35], v[34:35]
	v_pk_mul_f32 v[40:41], v[40:41], v[68:69] op_sel_hi:[1,0]
	v_pk_mul_f32 v[38:39], v[38:39], v[68:69] op_sel_hi:[1,0]
	v_pk_mul_f32 v[44:45], v[44:45], v[68:69] op_sel_hi:[1,0]
	v_pk_mul_f32 v[42:43], v[42:43], v[68:69] op_sel_hi:[1,0]
	v_pk_mul_f32 v[48:49], v[48:49], v[68:69] op_sel_hi:[1,0]
	v_pk_mul_f32 v[46:47], v[46:47], v[68:69] op_sel_hi:[1,0]
	v_pk_mul_f32 v[52:53], v[52:53], v[68:69] op_sel_hi:[1,0]
	v_pk_mul_f32 v[50:51], v[50:51], v[68:69] op_sel_hi:[1,0]
	v_pk_mul_f32 v[56:57], v[56:57], v[68:69] op_sel_hi:[1,0]
	v_pk_mul_f32 v[54:55], v[54:55], v[68:69] op_sel_hi:[1,0]
	v_pk_mul_f32 v[60:61], v[60:61], v[68:69] op_sel_hi:[1,0]
	v_pk_mul_f32 v[58:59], v[58:59], v[68:69] op_sel_hi:[1,0]
	v_pk_mul_f32 v[36:37], v[4:5], v[4:5]
	v_pk_fma_f32 v[8:9], v[8:9], v[66:67], v[40:41] op_sel_hi:[1,0,1] neg_lo:[0,0,1] neg_hi:[0,0,1]
	v_pk_fma_f32 v[38:39], v[6:7], v[66:67], v[38:39] op_sel_hi:[1,0,1] neg_lo:[0,0,1] neg_hi:[0,0,1]
	v_pk_fma_f32 v[12:13], v[12:13], v[66:67], v[44:45] op_sel_hi:[1,0,1] neg_lo:[0,0,1] neg_hi:[0,0,1]
	v_pk_fma_f32 v[10:11], v[10:11], v[66:67], v[42:43] op_sel_hi:[1,0,1] neg_lo:[0,0,1] neg_hi:[0,0,1]
	v_pk_fma_f32 v[16:17], v[16:17], v[66:67], v[48:49] op_sel_hi:[1,0,1] neg_lo:[0,0,1] neg_hi:[0,0,1]
	v_pk_fma_f32 v[14:15], v[14:15], v[66:67], v[46:47] op_sel_hi:[1,0,1] neg_lo:[0,0,1] neg_hi:[0,0,1]
	v_pk_fma_f32 v[20:21], v[20:21], v[66:67], v[52:53] op_sel_hi:[1,0,1] neg_lo:[0,0,1] neg_hi:[0,0,1]
	v_pk_fma_f32 v[18:19], v[18:19], v[66:67], v[50:51] op_sel_hi:[1,0,1] neg_lo:[0,0,1] neg_hi:[0,0,1]
	v_pk_fma_f32 v[24:25], v[24:25], v[66:67], v[56:57] op_sel_hi:[1,0,1] neg_lo:[0,0,1] neg_hi:[0,0,1]
	v_pk_fma_f32 v[22:23], v[22:23], v[66:67], v[54:55] op_sel_hi:[1,0,1] neg_lo:[0,0,1] neg_hi:[0,0,1]
	v_pk_fma_f32 v[28:29], v[28:29], v[66:67], v[60:61] op_sel_hi:[1,0,1] neg_lo:[0,0,1] neg_hi:[0,0,1]
	v_pk_fma_f32 v[26:27], v[26:27], v[66:67], v[58:59] op_sel_hi:[1,0,1] neg_lo:[0,0,1] neg_hi:[0,0,1]
	v_add_f32_e32 v66, v76, v77
	v_add_f32_e32 v36, v36, v66
	v_pk_mul_f32 v[6:7], v[38:39], v[38:39]
	v_add_f32_e32 v36, v37, v36
	v_add_f32_e32 v6, v6, v36
	v_pk_mul_f32 v[40:41], v[8:9], v[8:9]
	v_add_f32_e32 v6, v7, v6
	v_add_f32_e32 v6, v40, v6
	v_pk_mul_f32 v[42:43], v[10:11], v[10:11]
	v_add_f32_e32 v6, v41, v6
	v_add_f32_e32 v6, v42, v6
	v_pk_mul_f32 v[44:45], v[12:13], v[12:13]
	v_add_f32_e32 v6, v43, v6
	v_add_f32_e32 v6, v44, v6
	v_pk_mul_f32 v[46:47], v[14:15], v[14:15]
	v_add_f32_e32 v6, v45, v6
	v_add_f32_e32 v6, v46, v6
	v_pk_mul_f32 v[48:49], v[16:17], v[16:17]
	v_add_f32_e32 v6, v47, v6
	v_add_f32_e32 v6, v48, v6
	v_pk_mul_f32 v[50:51], v[18:19], v[18:19]
	v_add_f32_e32 v6, v49, v6
	v_add_f32_e32 v6, v50, v6
	v_pk_mul_f32 v[52:53], v[20:21], v[20:21]
	v_add_f32_e32 v6, v51, v6
	v_add_f32_e32 v6, v52, v6
	v_pk_mul_f32 v[54:55], v[22:23], v[22:23]
	v_add_f32_e32 v6, v53, v6
	v_add_f32_e32 v6, v54, v6
	v_pk_mul_f32 v[56:57], v[24:25], v[24:25]
	v_add_f32_e32 v6, v55, v6
	v_add_f32_e32 v6, v56, v6
	v_pk_mul_f32 v[58:59], v[26:27], v[26:27]
	v_add_f32_e32 v6, v57, v6
	v_add_f32_e32 v6, v58, v6
	v_pk_mul_f32 v[60:61], v[28:29], v[28:29]
	v_add_f32_e32 v6, v59, v6
	v_add_f32_e32 v6, v60, v6
	v_pk_mul_f32 v[70:71], v[30:31], v[30:31]
	v_add_f32_e32 v6, v61, v6
	v_add_f32_e32 v6, v70, v6
	v_pk_mul_f32 v[72:73], v[32:33], v[32:33]
	v_add_f32_e32 v6, v71, v6
	v_add_f32_e32 v6, v72, v6
	v_add_f32_e32 v6, v73, v6
	ds_bpermute_b32 v7, v229, v6
	v_lshl_add_u64 v[74:75], v[74:75], 0, v[214:215]
	v_lshl_add_u64 v[2:3], v[74:75], 0, s[10:11]
	s_waitcnt lgkmcnt(0)
	v_add_f32_e32 v6, v6, v7
	v_fmamk_f32 v6, v6, 0x3c800000, v192
	v_cmp_gt_f32_e32 vcc, s70, v6
	v_mul_f32_e32 v7, 0x4b800000, v6
	s_nop 0
	v_cndmask_b32_e32 v6, v6, v7, vcc
	v_rsq_f32_e32 v6, v6
	s_nop 0
	v_mul_f32_e32 v7, 0x45800000, v6
	v_cndmask_b32_e32 v6, v6, v7, vcc
	v_mul_f32_e32 v36, v233, v6
	v_pk_mul_f32 v[6:7], v[34:35], v[36:37] op_sel_hi:[1,0]
	v_pk_mul_f32 v[4:5], v[4:5], v[36:37] op_sel_hi:[1,0]
	s_waitcnt vmcnt(0)
	v_pk_mul_f32 v[6:7], v[62:63], v[6:7]
	v_pk_mul_f32 v[4:5], v[64:65], v[4:5]
	v_cvt_pk_bf16_f32 v6, v6, v7
	v_cvt_pk_bf16_f32 v7, v4, v5
	v_add_co_u32_e32 v4, vcc, s2, v74
	v_pk_mul_f32 v[34:35], v[38:39], v[36:37] op_sel_hi:[1,0]
	s_nop 0
	v_addc_co_u32_e32 v5, vcc, 0, v75, vcc
	global_store_dwordx2 v[4:5], v[6:7], off offset:1024
	v_pk_mul_f32 v[8:9], v[8:9], v[36:37] op_sel_hi:[1,0]
	v_mov_b64_e32 v[4:5], v[98:99]
	v_mov_b64_e32 v[6:7], v[100:101]
	v_pk_mul_f32 v[4:5], v[4:5], v[34:35]
	v_pk_mul_f32 v[6:7], v[6:7], v[8:9]
	v_cvt_pk_bf16_f32 v4, v4, v5
	v_cvt_pk_bf16_f32 v5, v6, v7
	global_store_dwordx2 v[2:3], v[4:5], off offset:16
	v_pk_mul_f32 v[8:9], v[10:11], v[36:37] op_sel_hi:[1,0]
	v_mov_b64_e32 v[4:5], v[102:103]
	v_mov_b64_e32 v[6:7], v[104:105]
	v_pk_mul_f32 v[4:5], v[4:5], v[8:9]
	v_pk_mul_f32 v[8:9], v[12:13], v[36:37] op_sel_hi:[1,0]
	v_cvt_pk_bf16_f32 v4, v4, v5
	v_pk_mul_f32 v[6:7], v[6:7], v[8:9]
	v_pk_mul_f32 v[8:9], v[14:15], v[36:37] op_sel_hi:[1,0]
	v_cvt_pk_bf16_f32 v5, v6, v7
	global_store_dwordx2 v[2:3], v[4:5], off offset:32
	v_mov_b64_e32 v[4:5], v[106:107]
	v_mov_b64_e32 v[6:7], v[108:109]
	v_pk_mul_f32 v[4:5], v[4:5], v[8:9]
	v_pk_mul_f32 v[8:9], v[16:17], v[36:37] op_sel_hi:[1,0]
	v_cvt_pk_bf16_f32 v4, v4, v5
	v_pk_mul_f32 v[6:7], v[6:7], v[8:9]
	v_pk_mul_f32 v[8:9], v[18:19], v[36:37] op_sel_hi:[1,0]
	v_cvt_pk_bf16_f32 v5, v6, v7
	global_store_dwordx2 v[2:3], v[4:5], off offset:48
	v_mov_b64_e32 v[4:5], v[110:111]
	v_mov_b64_e32 v[6:7], v[112:113]
	v_pk_mul_f32 v[4:5], v[4:5], v[8:9]
	v_pk_mul_f32 v[8:9], v[20:21], v[36:37] op_sel_hi:[1,0]
	v_cvt_pk_bf16_f32 v4, v4, v5
	v_pk_mul_f32 v[6:7], v[6:7], v[8:9]
	v_pk_mul_f32 v[8:9], v[22:23], v[36:37] op_sel_hi:[1,0]
	v_cvt_pk_bf16_f32 v5, v6, v7
	global_store_dwordx2 v[2:3], v[4:5], off offset:64
	v_mov_b64_e32 v[4:5], v[114:115]
	v_mov_b64_e32 v[6:7], v[116:117]
	v_pk_mul_f32 v[4:5], v[4:5], v[8:9]
	v_pk_mul_f32 v[8:9], v[24:25], v[36:37] op_sel_hi:[1,0]
	v_cvt_pk_bf16_f32 v4, v4, v5
	v_pk_mul_f32 v[6:7], v[6:7], v[8:9]
	v_pk_mul_f32 v[8:9], v[26:27], v[36:37] op_sel_hi:[1,0]
	v_cvt_pk_bf16_f32 v5, v6, v7
	global_store_dwordx2 v[2:3], v[4:5], off offset:80
	v_mov_b64_e32 v[4:5], v[122:123]
	v_mov_b64_e32 v[6:7], v[124:125]
	v_pk_mul_f32 v[4:5], v[4:5], v[8:9]
	v_pk_mul_f32 v[8:9], v[28:29], v[36:37] op_sel_hi:[1,0]
	v_cvt_pk_bf16_f32 v4, v4, v5
	v_pk_mul_f32 v[6:7], v[6:7], v[8:9]
	v_pk_mul_f32 v[8:9], v[30:31], v[36:37] op_sel_hi:[1,0]
	v_cvt_pk_bf16_f32 v5, v6, v7
	global_store_dwordx2 v[2:3], v[4:5], off offset:96
	v_mov_b64_e32 v[4:5], v[126:127]
	v_mov_b64_e32 v[6:7], v[128:129]
	v_pk_mul_f32 v[4:5], v[4:5], v[8:9]
	v_pk_mul_f32 v[8:9], v[32:33], v[36:37] op_sel_hi:[1,0]
	v_cvt_pk_bf16_f32 v4, v4, v5
	v_pk_mul_f32 v[6:7], v[6:7], v[8:9]
	s_nop 0
	v_cvt_pk_bf16_f32 v5, v6, v7
	global_store_dwordx2 v[2:3], v[4:5], off offset:112
	s_cbranch_scc0 .LBB0_745
